# P10: final y stores non-temporal (nt) instead of write-through
# speedup vs baseline: 1.0084x; 1.0010x over previous
.LBB0_1323:
	s_waitcnt vmcnt(21)
	v_lshlrev_b32_e32 v148, 16, v138
	v_and_b32_e32 v149, 0xffff0000, v138
	v_lshlrev_b32_e32 v138, 16, v139
	v_and_b32_e32 v139, 0xffff0000, v139
	v_mul_f32_e32 v150, v139, v139
	s_waitcnt vmcnt(20)
	v_lshlrev_b32_e32 v153, 16, v137
	v_lshlrev_b32_e32 v152, 16, v136
	v_and_b32_e32 v137, 0xffff0000, v137
	v_and_b32_e32 v136, 0xffff0000, v136
	s_waitcnt vmcnt(18)
	v_lshlrev_b32_e32 v159, 16, v132
	v_mul_f32_e32 v158, v149, v149
	v_pk_fma_f32 v[150:151], v[138:139], v[138:139], v[150:151] op_sel_hi:[1,1,0]
	v_pk_mul_f32 v[154:155], v[136:137], v[136:137]
	v_pk_fma_f32 v[162:163], v[148:149], v[148:149], v[158:159] op_sel_hi:[1,1,0]
	v_pk_fma_f32 v[154:155], v[152:153], v[152:153], v[154:155]
	v_and_b32_e32 v161, 0xffff0000, v132
	v_mov_b32_e32 v158, v162
	v_mov_b32_e32 v164, v150
	v_mov_b32_e32 v165, v159
	v_mul_f32_e32 v147, v161, v161
	v_pk_add_f32 v[150:151], v[162:163], v[150:151]
	v_pk_mul_f32 v[162:163], v[158:159], v[164:165]
	v_pk_add_f32 v[154:155], v[154:155], v[154:155] op_sel:[0,1] op_sel_hi:[1,0]
	v_lshlrev_b32_e32 v156, 16, v134
	v_and_b32_e32 v157, 0xffff0000, v134
	v_lshlrev_b32_e32 v134, 16, v135
	v_and_b32_e32 v135, 0xffff0000, v135
	v_mov_b32_e32 v151, v163
	v_mov_b32_e32 v155, v147
	v_lshlrev_b32_e32 v132, 16, v133
	v_and_b32_e32 v133, 0xffff0000, v133
	v_pk_add_f32 v[150:151], v[150:151], v[154:155]
	v_mul_f32_e32 v154, v157, v157
	v_mul_f32_e32 v158, v135, v135
	v_mul_f32_e32 v160, v132, v132
	v_mul_f32_e32 v166, v133, v133
	v_pk_fma_f32 v[154:155], v[156:157], v[156:157], v[154:155] op_sel_hi:[1,1,0]
	v_pk_fma_f32 v[162:163], v[134:135], v[134:135], v[158:159] op_sel_hi:[1,1,0]
	v_mov_b32_e32 v155, v160
	v_mov_b32_e32 v163, v166
	v_pk_add_f32 v[154:155], v[154:155], v[162:163]
	s_waitcnt vmcnt(7)
	v_lshlrev_b32_e32 v165, 16, v129
	v_pk_add_f32 v[150:151], v[150:151], v[154:155]
	v_lshlrev_b32_e32 v155, 16, v131
	v_lshlrev_b32_e32 v154, 16, v130
	v_and_b32_e32 v131, 0xffff0000, v131
	v_and_b32_e32 v130, 0xffff0000, v130
	v_pk_mul_f32 v[162:163], v[130:131], v[130:131]
	v_lshlrev_b32_e32 v164, 16, v128
	v_pk_fma_f32 v[162:163], v[154:155], v[154:155], v[162:163]
	v_and_b32_e32 v129, 0xffff0000, v129
	v_pk_add_f32 v[162:163], v[162:163], v[162:163] op_sel:[0,1] op_sel_hi:[1,0]
	v_and_b32_e32 v128, 0xffff0000, v128
	s_waitcnt vmcnt(5)
	v_lshlrev_b32_e32 v171, 16, v124
	v_pk_add_f32 v[150:151], v[150:151], v[150:151] op_sel:[0,1] op_sel_hi:[1,0]
	v_pk_mul_f32 v[166:167], v[128:129], v[128:129]
	v_mov_b32_e32 v170, v150
	v_mov_b32_e32 v174, v162
	v_mov_b32_e32 v175, v171
	v_pk_fma_f32 v[166:167], v[164:165], v[164:165], v[166:167]
	v_and_b32_e32 v173, 0xffff0000, v124
	v_pk_add_f32 v[150:151], v[150:151], v[162:163]
	v_pk_mul_f32 v[162:163], v[170:171], v[174:175]
	v_and_b32_e32 v169, 0xffff0000, v126
	v_mul_f32_e32 v147, v173, v173
	v_mov_b32_e32 v151, v163
	v_pk_add_f32 v[162:163], v[166:167], v[166:167] op_sel:[0,1] op_sel_hi:[1,0]
	v_lshlrev_b32_e32 v168, 16, v126
	v_lshlrev_b32_e32 v126, 16, v127
	v_and_b32_e32 v127, 0xffff0000, v127
	v_mov_b32_e32 v163, v147
	v_mul_f32_e32 v158, v169, v169
	v_lshlrev_b32_e32 v124, 16, v125
	v_and_b32_e32 v125, 0xffff0000, v125
	v_pk_add_f32 v[150:151], v[150:151], v[162:163]
	v_pk_fma_f32 v[162:163], v[168:169], v[168:169], v[158:159] op_sel_hi:[1,1,0]
	v_mul_f32_e32 v158, v127, v127
	v_mul_f32_e32 v160, v124, v124
	v_mul_f32_e32 v172, v125, v125
	v_pk_fma_f32 v[166:167], v[126:127], v[126:127], v[158:159] op_sel_hi:[1,1,0]
	v_mov_b32_e32 v163, v160
	v_mov_b32_e32 v167, v172
	v_pk_add_f32 v[162:163], v[162:163], v[166:167]
	v_mov_b32_e32 v160, v159
	v_pk_add_f32 v[150:151], v[150:151], v[162:163]
	v_lshlrev_b32_e32 v162, 16, v122
	v_add_f32_e32 v147, v150, v151
	ds_bpermute_b32 v150, v140, v147
	v_and_b32_e32 v163, 0xffff0000, v122
	v_lshlrev_b32_e32 v122, 16, v123
	v_and_b32_e32 v123, 0xffff0000, v123
	v_mov_b32_e32 v172, v171
	s_waitcnt lgkmcnt(0)
	v_add_f32_e32 v147, v147, v150
	ds_bpermute_b32 v150, v141, v147
	s_waitcnt lgkmcnt(0)
	v_add_f32_e32 v147, v147, v150
	ds_bpermute_b32 v150, v142, v147
	s_waitcnt lgkmcnt(0)
	v_add_f32_e32 v147, v147, v150
	ds_bpermute_b32 v150, v143, v147
	s_waitcnt lgkmcnt(0)
	v_add_f32_e32 v147, v147, v150
	ds_bpermute_b32 v150, v144, v147
	s_waitcnt lgkmcnt(0)
	v_add_f32_e32 v147, v147, v150
	ds_bpermute_b32 v150, v145, v147
	s_waitcnt lgkmcnt(0)
	v_add_f32_e32 v147, v147, v150
	v_fmamk_f32 v147, v147, 0x3a000000, v146
	v_mul_f32_e32 v150, 0x4b800000, v147
	v_cmp_gt_f32_e32 vcc, s17, v147
	s_nop 1
	v_cndmask_b32_e32 v147, v147, v150, vcc
	v_rsq_f32_e32 v147, v147
	s_nop 0
	v_mul_f32_e32 v150, 0x45800000, v147
	v_cndmask_b32_e32 v150, v147, v150, vcc
	v_pk_mul_f32 v[148:149], v[150:151], v[148:149] op_sel_hi:[0,1]
	v_pk_mul_f32 v[138:139], v[150:151], v[138:139] op_sel_hi:[0,1]
	v_pk_fma_f32 v[62:63], v[62:63], v[138:139], v[122:123]
	v_pk_fma_f32 v[60:61], v[60:61], v[148:149], v[162:163]
	global_store_dwordx4 v[72:73], v[60:63], off offset:-4096 nt
	s_andn2_b64 vcc, exec, s[12:13]
	s_nop 0
	v_lshlrev_b32_e32 v60, 16, v120
	v_and_b32_e32 v61, 0xffff0000, v120
	v_lshlrev_b32_e32 v62, 16, v121
	v_and_b32_e32 v63, 0xffff0000, v121
	v_mov_b32_e32 v120, v152
	v_mov_b32_e32 v121, v136
	v_mov_b32_e32 v136, v153
	v_pk_mul_f32 v[120:121], v[150:151], v[120:121] op_sel_hi:[0,1]
	v_pk_mul_f32 v[122:123], v[150:151], v[136:137] op_sel_hi:[0,1]
	v_pk_fma_f32 v[58:59], v[58:59], v[122:123], v[62:63]
	v_pk_fma_f32 v[56:57], v[56:57], v[120:121], v[60:61]
	global_store_dwordx4 v[72:73], v[56:59], off offset:-3072 nt
	v_pk_mul_f32 v[60:61], v[150:151], v[156:157] op_sel_hi:[0,1]
	v_pk_mul_f32 v[62:63], v[150:151], v[134:135] op_sel_hi:[0,1]
	v_lshlrev_b32_e32 v56, 16, v118
	v_and_b32_e32 v57, 0xffff0000, v118
	v_lshlrev_b32_e32 v58, 16, v119
	v_and_b32_e32 v59, 0xffff0000, v119
	v_pk_fma_f32 v[54:55], v[54:55], v[62:63], v[58:59]
	v_pk_fma_f32 v[52:53], v[52:53], v[60:61], v[56:57]
	global_store_dwordx4 v[72:73], v[52:55], off offset:-2048 nt
	v_pk_mul_f32 v[56:57], v[160:161], v[150:151] op_sel_hi:[1,0]
	v_pk_mul_f32 v[58:59], v[132:133], v[150:151] op_sel_hi:[1,0]
	v_lshlrev_b32_e32 v52, 16, v116
	v_and_b32_e32 v53, 0xffff0000, v116
	v_lshlrev_b32_e32 v54, 16, v117
	v_and_b32_e32 v55, 0xffff0000, v117
	v_pk_fma_f32 v[50:51], v[50:51], v[58:59], v[54:55]
	v_pk_fma_f32 v[48:49], v[48:49], v[56:57], v[52:53]
	v_mov_b32_e32 v52, v154
	v_mov_b32_e32 v53, v130
	v_mov_b32_e32 v130, v155
	global_store_dwordx4 v[72:73], v[48:51], off offset:-1024 nt
	v_pk_mul_f32 v[52:53], v[150:151], v[52:53] op_sel_hi:[0,1]
	v_pk_mul_f32 v[54:55], v[150:151], v[130:131] op_sel_hi:[0,1]
	s_waitcnt vmcnt(8)
	v_lshlrev_b32_e32 v48, 16, v114
	v_and_b32_e32 v49, 0xffff0000, v114
	v_lshlrev_b32_e32 v50, 16, v115
	v_and_b32_e32 v51, 0xffff0000, v115
	v_pk_fma_f32 v[46:47], v[46:47], v[54:55], v[50:51]
	v_pk_fma_f32 v[44:45], v[44:45], v[52:53], v[48:49]
	v_mov_b32_e32 v48, v164
	v_mov_b32_e32 v49, v128
	v_mov_b32_e32 v128, v165
	global_store_dwordx4 v[72:73], v[44:47], off nt
	v_pk_mul_f32 v[48:49], v[150:151], v[48:49] op_sel_hi:[0,1]
	v_pk_mul_f32 v[50:51], v[150:151], v[128:129] op_sel_hi:[0,1]
	s_waitcnt vmcnt(8)
	v_lshlrev_b32_e32 v44, 16, v112
	v_and_b32_e32 v45, 0xffff0000, v112
	v_lshlrev_b32_e32 v46, 16, v113
	v_and_b32_e32 v47, 0xffff0000, v113
	v_pk_fma_f32 v[42:43], v[42:43], v[50:51], v[46:47]
	v_pk_fma_f32 v[40:41], v[40:41], v[48:49], v[44:45]
	global_store_dwordx4 v[72:73], v[40:43], off offset:1024 nt
	v_pk_mul_f32 v[44:45], v[150:151], v[168:169] op_sel_hi:[0,1]
	v_pk_mul_f32 v[46:47], v[150:151], v[126:127] op_sel_hi:[0,1]
	s_waitcnt vmcnt(8)
	v_lshlrev_b32_e32 v40, 16, v110
	v_and_b32_e32 v41, 0xffff0000, v110
	v_lshlrev_b32_e32 v42, 16, v111
	v_and_b32_e32 v43, 0xffff0000, v111
	v_pk_fma_f32 v[38:39], v[38:39], v[46:47], v[42:43]
	v_pk_fma_f32 v[36:37], v[36:37], v[44:45], v[40:41]
	global_store_dwordx4 v[72:73], v[36:39], off offset:2048 nt
	v_pk_mul_f32 v[40:41], v[172:173], v[150:151] op_sel_hi:[1,0]
	v_pk_mul_f32 v[42:43], v[124:125], v[150:151] op_sel_hi:[1,0]
	s_waitcnt vmcnt(8)
	v_lshlrev_b32_e32 v36, 16, v108
	v_and_b32_e32 v37, 0xffff0000, v108
	v_lshlrev_b32_e32 v38, 16, v109
	v_and_b32_e32 v39, 0xffff0000, v109
	s_waitcnt vmcnt(7)
	v_pk_fma_f32 v[34:35], v[34:35], v[42:43], v[38:39]
	v_pk_fma_f32 v[32:33], v[32:33], v[40:41], v[36:37]
	global_store_dwordx4 v[72:73], v[32:35], off offset:3072 nt
	s_cbranch_vccnz .LBB0_1320
	v_and_b32_e32 v39, 0xffff0000, v82
	v_and_b32_e32 v38, 0xffff0000, v80
	v_and_b32_e32 v43, 0xffff0000, v83
	v_and_b32_e32 v42, 0xffff0000, v81
	v_lshlrev_b32_e32 v37, 16, v82
	v_lshlrev_b32_e32 v36, 16, v80
	v_lshlrev_b32_e32 v41, 16, v83
	v_lshlrev_b32_e32 v40, 16, v81
	v_pk_mul_f32 v[32:33], v[38:39], v[38:39]
	v_pk_mul_f32 v[34:35], v[42:43], v[42:43]
	v_pk_fma_f32 v[32:33], v[36:37], v[36:37], v[32:33]
	v_pk_fma_f32 v[34:35], v[40:41], v[40:41], v[34:35]
	v_and_b32_e32 v47, 0xffff0000, v79
	v_pk_add_f32 v[32:33], v[32:33], v[34:35]
	v_and_b32_e32 v46, 0xffff0000, v78
	v_pk_add_f32 v[32:33], v[32:33], v[32:33] op_sel_hi:[0,1]
	v_lshlrev_b32_e32 v45, 16, v79
	v_lshlrev_b32_e32 v44, 16, v78
	v_pk_mul_f32 v[34:35], v[46:47], v[46:47]
	v_lshlrev_b32_e32 v48, 16, v76
	v_and_b32_e32 v49, 0xffff0000, v76
	v_lshlrev_b32_e32 v54, 16, v77
	v_lshlrev_b32_e32 v50, 16, v96
	v_pk_fma_f32 v[34:35], v[44:45], v[44:45], v[34:35]
	v_mul_f32_e32 v51, v48, v48
	v_mul_f32_e32 v53, v49, v49
	v_and_b32_e32 v55, 0xffff0000, v77
	v_mul_f32_e32 v32, v54, v54
	v_mov_b32_e32 v52, v50
	v_pk_add_f32 v[34:35], v[34:35], v[34:35] op_sel_hi:[0,1]
	v_pk_fma_f32 v[56:57], v[54:55], v[54:55], v[32:33] op_sel_hi:[1,1,0]
	v_and_b32_e32 v120, 0xffff0000, v96
	v_lshlrev_b32_e32 v58, 16, v97
	v_and_b32_e32 v59, 0xffff0000, v97
	v_pk_add_f32 v[52:53], v[50:51], v[52:53]
	v_mul_f32_e32 v56, v120, v120
	v_mul_f32_e32 v34, v58, v58
	v_mul_f32_e32 v32, v59, v59
	v_mul_f32_e32 v60, v50, v50
	v_mov_b32_e32 v61, v53
	v_pk_add_f32 v[52:53], v[60:61], v[56:57]
	v_pk_add_f32 v[32:33], v[34:35], v[32:33]
	v_and_b32_e32 v57, 0xffff0000, v95
	v_pk_add_f32 v[32:33], v[52:53], v[32:33]
	v_and_b32_e32 v56, 0xffff0000, v94
	v_pk_add_f32 v[32:33], v[32:33], v[32:33] op_sel_hi:[0,1]
	v_lshlrev_b32_e32 v53, 16, v95
	v_lshlrev_b32_e32 v52, 16, v94
	v_pk_mul_f32 v[34:35], v[56:57], v[56:57]
	v_lshlrev_b32_e32 v60, 16, v92
	v_and_b32_e32 v61, 0xffff0000, v92
	v_lshlrev_b32_e32 v110, 16, v93
	v_lshlrev_b32_e32 v62, 16, v98
	v_pk_fma_f32 v[34:35], v[52:53], v[52:53], v[34:35]
	v_mul_f32_e32 v63, v60, v60
	v_mul_f32_e32 v109, v61, v61
	v_and_b32_e32 v111, 0xffff0000, v93
	v_mul_f32_e32 v32, v110, v110
	v_mov_b32_e32 v108, v62
	v_pk_add_f32 v[34:35], v[34:35], v[34:35] op_sel_hi:[0,1]
	v_pk_fma_f32 v[112:113], v[110:111], v[110:111], v[32:33] op_sel_hi:[1,1,0]
	v_and_b32_e32 v121, 0xffff0000, v98
	v_lshlrev_b32_e32 v114, 16, v99
	v_and_b32_e32 v115, 0xffff0000, v99
	v_pk_add_f32 v[108:109], v[62:63], v[108:109]
	v_mul_f32_e32 v112, v121, v121
	v_mul_f32_e32 v34, v114, v114
	v_mul_f32_e32 v32, v115, v115
	v_mul_f32_e32 v116, v62, v62
	v_mov_b32_e32 v117, v109
	v_pk_add_f32 v[108:109], v[116:117], v[112:113]
	v_pk_add_f32 v[32:33], v[34:35], v[32:33]
	s_ashr_i32 s11, s10, 31
	v_pk_add_f32 v[32:33], v[108:109], v[32:33]
	v_mov_b32_e32 v116, v37
	v_add_f32_e32 v32, v32, v33
	ds_bpermute_b32 v33, v140, v32
	v_mov_b32_e32 v117, v39
	v_mov_b32_e32 v118, v41
	v_mov_b32_e32 v119, v43
	s_lshl_b64 s[10:11], s[10:11], 13
	s_waitcnt lgkmcnt(0)
	v_add_f32_e32 v32, v32, v33
	ds_bpermute_b32 v33, v141, v32
	v_lshlrev_b32_e32 v34, 16, v91
	v_and_b32_e32 v35, 0xffff0000, v91
	v_lshl_add_u64 v[108:109], v[70:71], 0, s[10:11]
	v_mov_b32_e32 v37, v38
	s_waitcnt lgkmcnt(0)
	v_add_f32_e32 v32, v32, v33
	ds_bpermute_b32 v33, v142, v32
	v_mov_b32_e32 v41, v42
	v_mov_b32_e32 v51, v120
	v_mov_b32_e32 v63, v121
	s_waitcnt lgkmcnt(0)
	v_add_f32_e32 v32, v32, v33
	ds_bpermute_b32 v33, v143, v32
	s_waitcnt lgkmcnt(0)
	v_add_f32_e32 v32, v32, v33
	ds_bpermute_b32 v33, v144, v32
	s_waitcnt lgkmcnt(0)
	v_add_f32_e32 v32, v32, v33
	ds_bpermute_b32 v33, v145, v32
	s_waitcnt lgkmcnt(0)
	v_add_f32_e32 v32, v32, v33
	v_fmamk_f32 v32, v32, 0x3a000000, v146
	v_mul_f32_e32 v33, 0x4b800000, v32
	v_cmp_gt_f32_e32 vcc, s17, v32
	s_nop 1
	v_cndmask_b32_e32 v32, v32, v33, vcc
	v_rsq_f32_e32 v32, v32
	s_nop 0
	v_mul_f32_e32 v33, 0x45800000, v32
	v_cndmask_b32_e32 v112, v32, v33, vcc
	v_lshlrev_b32_e32 v32, 16, v90
	v_and_b32_e32 v33, 0xffff0000, v90
	v_pk_mul_f32 v[116:117], v[116:117], v[112:113] op_sel_hi:[1,0]
	v_pk_mul_f32 v[118:119], v[118:119], v[112:113] op_sel_hi:[1,0]
	v_pk_fma_f32 v[32:33], v[12:13], v[116:117], v[32:33]
	v_pk_fma_f32 v[34:35], v[14:15], v[118:119], v[34:35]
	global_store_dwordx4 v[108:109], v[32:35], off nt
	v_pk_mul_f32 v[36:37], v[36:37], v[112:113] op_sel_hi:[1,0]
	v_pk_mul_f32 v[38:39], v[40:41], v[112:113] op_sel_hi:[1,0]
	v_lshlrev_b32_e32 v32, 16, v88
	v_and_b32_e32 v33, 0xffff0000, v88
	v_lshlrev_b32_e32 v34, 16, v89
	v_and_b32_e32 v35, 0xffff0000, v89
	v_pk_fma_f32 v[34:35], v[2:3], v[38:39], v[34:35]
	v_pk_fma_f32 v[32:33], v[0:1], v[36:37], v[32:33]
	v_mov_b32_e32 v36, v44
	v_mov_b32_e32 v37, v46
	v_mov_b32_e32 v46, v45
	global_store_dwordx4 v[108:109], v[32:35], off offset:1024 nt
	v_pk_mul_f32 v[36:37], v[112:113], v[36:37] op_sel_hi:[0,1]
	v_pk_mul_f32 v[38:39], v[112:113], v[46:47] op_sel_hi:[0,1]
	v_lshlrev_b32_e32 v32, 16, v86
	v_and_b32_e32 v33, 0xffff0000, v86
	v_lshlrev_b32_e32 v34, 16, v87
	v_and_b32_e32 v35, 0xffff0000, v87
	v_pk_fma_f32 v[34:35], v[6:7], v[38:39], v[34:35]
	v_pk_fma_f32 v[32:33], v[4:5], v[36:37], v[32:33]
	global_store_dwordx4 v[108:109], v[32:35], off offset:2048 nt
	v_pk_mul_f32 v[36:37], v[48:49], v[112:113] op_sel_hi:[1,0]
	v_pk_mul_f32 v[38:39], v[54:55], v[112:113] op_sel_hi:[1,0]
	v_lshlrev_b32_e32 v32, 16, v84
	v_and_b32_e32 v33, 0xffff0000, v84
	v_lshlrev_b32_e32 v34, 16, v85
	v_and_b32_e32 v35, 0xffff0000, v85
	v_pk_fma_f32 v[34:35], v[10:11], v[38:39], v[34:35]
	v_pk_fma_f32 v[32:33], v[8:9], v[36:37], v[32:33]
	global_store_dwordx4 v[108:109], v[32:35], off offset:3072 nt
	v_pk_mul_f32 v[36:37], v[50:51], v[112:113] op_sel_hi:[1,0]
	v_pk_mul_f32 v[38:39], v[58:59], v[112:113] op_sel_hi:[1,0]
	v_lshlrev_b32_e32 v32, 16, v106
	v_and_b32_e32 v33, 0xffff0000, v106
	v_lshlrev_b32_e32 v34, 16, v107
	v_and_b32_e32 v35, 0xffff0000, v107
	v_pk_fma_f32 v[32:33], v[16:17], v[36:37], v[32:33]
	v_add_co_u32_e32 v36, vcc, s18, v108
	v_pk_fma_f32 v[34:35], v[18:19], v[38:39], v[34:35]
	s_nop 0
	v_addc_co_u32_e32 v37, vcc, 0, v109, vcc
	v_mov_b32_e32 v38, v52
	v_mov_b32_e32 v39, v56
	v_mov_b32_e32 v56, v53
	global_store_dwordx4 v[36:37], v[32:35], off nt
	v_pk_mul_f32 v[38:39], v[112:113], v[38:39] op_sel_hi:[0,1]
	v_pk_mul_f32 v[40:41], v[112:113], v[56:57] op_sel_hi:[0,1]
	v_lshlrev_b32_e32 v32, 16, v104
	v_and_b32_e32 v33, 0xffff0000, v104
	v_lshlrev_b32_e32 v34, 16, v105
	v_and_b32_e32 v35, 0xffff0000, v105
	v_pk_fma_f32 v[34:35], v[22:23], v[40:41], v[34:35]
	v_pk_fma_f32 v[32:33], v[20:21], v[38:39], v[32:33]
	global_store_dwordx4 v[36:37], v[32:35], off offset:1024 nt
	v_pk_mul_f32 v[38:39], v[60:61], v[112:113] op_sel_hi:[1,0]
	v_pk_mul_f32 v[40:41], v[110:111], v[112:113] op_sel_hi:[1,0]
	v_lshlrev_b32_e32 v32, 16, v102
	v_and_b32_e32 v33, 0xffff0000, v102
	v_lshlrev_b32_e32 v34, 16, v103
	v_and_b32_e32 v35, 0xffff0000, v103
	v_pk_fma_f32 v[34:35], v[30:31], v[40:41], v[34:35]
	v_pk_fma_f32 v[32:33], v[28:29], v[38:39], v[32:33]
	global_store_dwordx4 v[36:37], v[32:35], off offset:2048 nt
	v_pk_mul_f32 v[38:39], v[62:63], v[112:113] op_sel_hi:[1,0]
	v_pk_mul_f32 v[40:41], v[114:115], v[112:113] op_sel_hi:[1,0]
	v_lshlrev_b32_e32 v32, 16, v100
	v_and_b32_e32 v33, 0xffff0000, v100
	v_lshlrev_b32_e32 v34, 16, v101
	v_and_b32_e32 v35, 0xffff0000, v101
	v_pk_fma_f32 v[34:35], v[26:27], v[40:41], v[34:35]
	v_pk_fma_f32 v[32:33], v[24:25], v[38:39], v[32:33]
	global_store_dwordx4 v[36:37], v[32:35], off offset:3072 nt
	s_branch .LBB0_1320
